# GA loop: static s_setprio 1 for the older half (waves 0-3), per-segment flips deleted, on the interleaved loop
# baseline (speedup 1.0000x reference)
.LBB0_1273:
	s_andn2_b64 vcc, exec, s[0:1]
	s_cbranch_vccnz .LBB0_1287
	s_lshl_b32 s0, s22, 1
	s_addk_i32 s0, 0xfeb0
	v_mov_b32_e32 v20, v201
	v_add_u32_e32 v8, s0, v149
	v_lshlrev_b32_e32 v0, 6, v8
	v_lshrrev_b32_e32 v6, 1, v20
	v_and_b32_e32 v2, 32, v6
	s_movk_i32 s0, 0xfc0
	v_ashrrev_i32_e32 v106, 7, v8
	v_bfe_u32 v5, v8, 6, 1
	v_and_or_b32 v0, v0, s0, v2
	v_mov_b64_e32 v[2:3], s[42:43]
	s_mov_b32 s0, 0x220000
	v_mad_i64_i32 v[2:3], s[0:1], v106, s0, v[2:3]
	v_lshlrev_b32_e32 v4, 7, v5
	v_and_or_b32 v110, v6, 64, v4
	v_mov_b64_e32 v[6:7], s[58:59]
	s_mov_b32 s0, 0x110000
	v_add_u32_e32 v108, 0x100, v0
	v_lshlrev_b32_e32 v0, 1, v110
	v_mad_i64_i32 v[6:7], s[0:1], v106, s0, v[6:7]
	v_and_b32_e32 v107, 15, v20
	v_bfe_u32 v21, v20, 4, 2
	v_lshl_add_u64 v[2:3], v[2:3], 0, v[0:1]
	v_lshlrev_b32_e32 v0, 6, v5
	v_mov_b32_e32 v5, v1
	s_movk_i32 s0, 0xff80
	v_lshl_add_u64 v[4:5], v[6:7], 0, v[4:5]
	v_and_or_b32 v6, v8, s0, v0
	v_or_b32_e32 v7, v108, v107
	v_lshlrev_b32_e32 v0, 4, v21
	v_lshl_add_u64 v[2:3], v[2:3], 0, v[0:1]
	v_lshlrev_b32_e32 v0, 9, v7
	v_lshl_add_u64 v[2:3], v[2:3], 0, v[0:1]
	s_movk_i32 s0, 0x2000
	global_load_dwordx4 v[46:49], v[2:3], off
	global_load_dwordx4 v[42:45], v[2:3], off offset:64
	v_add_co_u32_e32 v2, vcc, s0, v2
	v_and_b32_e32 v22, 7, v20
	s_nop 0
	v_addc_co_u32_e32 v3, vcc, 0, v3, vcc
	global_load_dwordx4 v[50:53], v[2:3], off
	global_load_dwordx4 v[54:57], v[2:3], off offset:64
	v_mov_b64_e32 v[2:3], s[44:45]
	v_bfe_u32 v126, v20, 3, 5
	v_lshlrev_b32_e32 v114, 4, v22
	v_mov_b32_e32 v115, v1
	v_mad_i64_i32 v[2:3], s[0:1], v6, s85, v[2:3]
	v_lshl_add_u64 v[116:117], v[4:5], 0, v[114:115]
	v_lshlrev_b32_e32 v0, 8, v126
	v_or_b32_e32 v23, 32, v126
	v_lshl_add_u64 v[18:19], v[2:3], 0, v[114:115]
	v_lshl_add_u64 v[2:3], v[116:117], 0, v[0:1]
	v_lshlrev_b32_e32 v0, 8, v23
	v_mad_u64_u32 v[6:7], s[0:1], v126, s85, v[18:19]
	v_lshl_add_u64 v[10:11], v[116:117], 0, v[0:1]
	v_mad_u64_u32 v[14:15], s[0:1], v23, s85, v[18:19]
	v_mov_b32 v122, 0xc2800000
	global_load_dwordx4 v[2:5], v[2:3], off
	s_nop 0
	global_load_dwordx4 v[6:9], v[6:7], off
	s_nop 0
	global_load_dwordx4 v[10:13], v[10:11], off
	s_nop 0
	global_load_dwordx4 v[14:17], v[14:15], off
	v_lshrrev_b32_e32 v26, 3, v20
	v_lshrrev_b32_e32 v25, 4, v20
	v_xor_b32_e32 v20, v26, v20
	v_lshlrev_b32_e32 v20, 4, v20
	v_and_b32_e32 v132, 0x70, v20
	v_lshlrev_b32_e32 v112, 3, v21
	v_lshlrev_b32_e32 v127, 7, v126
	v_bitop3_b32 v21, v21, v22, 4 bitop3:0x36
	v_add_u32_e32 v20, v150, v132
	v_and_b32_e32 v24, 64, v208
	v_mul_u32_u24_e32 v128, 0x90, v126
	v_lshlrev_b32_e32 v131, 7, v23
	v_lshlrev_b32_e32 v129, 4, v21
	v_add_u32_e32 v21, v20, v127
	v_xor_b32_e32 v0, 16, v208
	v_bitop3_b32 v25, v25, v22, 3 bitop3:0x6c
	v_add3_u32 v22, v150, v114, v128
	v_add_u32_e32 v20, v20, v131
	v_lshlrev_b32_e32 v130, 4, v25
	v_mov_b32_e32 v38, 0
	s_mov_b32 s0, 0
	v_lshlrev_b32_e32 v115, 7, v107
	v_mov_b32_e32 v123, v122
	v_mov_b32_e32 v165, 0
	v_mov_b32_e32 v152, 0x42800000
	v_mov_b32_e32 v153, v152
	v_mov_b32_e32 v154, v152
	v_mov_b32_e32 v155, v152
	v_mov_b32_e32 v156, v152
	v_mov_b32_e32 v157, v152
	v_mov_b32_e32 v158, v152
	v_mov_b32_e32 v159, v152
	v_mul_u32_u24_e32 v109, 0x90, v107
	v_mov_b32_e32 v39, v38
	v_mov_b32_e32 v40, v38
	v_mov_b32_e32 v41, v38
	v_mov_b32_e32 v34, v38
	v_mov_b32_e32 v35, v38
	v_mov_b32_e32 v36, v38
	v_mov_b32_e32 v37, v38
	s_waitcnt vmcnt(0) lgkmcnt(0)
	ds_write_b128 v21, v[2:5]
	ds_write_b128 v22, v[6:9] offset:8192
	ds_write_b128 v20, v[10:13]
	ds_write_b128 v22, v[14:17] offset:12800
	v_add_u32_e32 v2, 64, v24
	v_cmp_lt_i32_e32 vcc, v0, v2
	v_mov_b32_e32 v3, v1
	s_waitcnt lgkmcnt(0)
	v_cndmask_b32_e32 v0, v208, v0, vcc
	v_lshlrev_b32_e32 v111, 2, v0
	v_xor_b32_e32 v0, 32, v208
	v_cmp_lt_i32_e32 vcc, v0, v2
	v_mov_b32_e32 v2, v1
	s_barrier
	v_cndmask_b32_e32 v0, v208, v0, vcc
	v_lshlrev_b32_e32 v113, 2, v0
	v_mul_u32_u24_e32 v0, 0x1100, v126
	v_lshlrev_b32_e32 v0, 1, v0
	v_lshl_add_u64 v[120:121], v[18:19], 0, v[0:1]
	v_mov_b32_e32 v0, v1
	v_mov_b64_e32 v[20:21], v[2:3]
	v_mov_b64_e32 v[24:25], v[2:3]
	v_mov_b64_e32 v[28:29], v[2:3]
	v_mov_b64_e32 v[32:33], v[2:3]
	v_mov_b64_e32 v[12:13], v[2:3]
	v_mov_b64_e32 v[16:17], v[2:3]
	v_mov_b64_e32 v[8:9], v[2:3]
	v_mov_b64_e32 v[18:19], v[0:1]
	v_mov_b64_e32 v[22:23], v[0:1]
	v_mov_b64_e32 v[26:27], v[0:1]
	v_mov_b64_e32 v[30:31], v[0:1]
	v_mov_b64_e32 v[10:11], v[0:1]
	v_mov_b64_e32 v[14:15], v[0:1]
	v_mov_b64_e32 v[6:7], v[0:1]
	v_mov_b64_e32 v[4:5], v[2:3]
	v_mov_b64_e32 v[2:3], v[0:1]
	v_add_u32_e32 v170, v150, v115
	v_add_u32_e32 v171, v170, v129
	v_add_u32_e32 v170, v170, v130
	v_add3_u32 v172, v150, v109, v112
	v_add_u32_e32 v173, 0x2800, v172
	v_add_u32_e32 v174, 0x6400, v172
	v_add_u32_e32 v175, 0x6c00, v172
	v_add_u32_e32 v176, 0x3000, v172
	v_add_u32_e32 v177, 0x3800, v172
	v_add_u32_e32 v178, 0x7400, v172
	v_add_u32_e32 v179, 0x7c00, v172
	v_add_u32_e32 v172, 0x2000, v172
	v_add_u32_e32 v180, v150, v132
	v_add_u32_e32 v181, v180, v131
	v_add_u32_e32 v180, v180, v127
	v_add3_u32 v182, v150, v114, v128
	v_lshlrev_b32_e32 v164, 8, v126
	v_lshl_add_u64 v[184:185], v[116:117], 0, v[164:165]
	s_mov_b64 s[2:3], 0x2000
	v_lshl_add_u64 v[186:187], v[184:185], 0, s[2:3]
	s_mov_b64 s[2:3], 0x44000
	v_lshl_add_u64 v[188:189], v[120:121], 0, s[2:3]
	v_mov_b32_e32 v190, s36
	v_mov_b32_e32 v191, s36
	v_mov_b32_e32 v192, s36
	v_mov_b32_e32 v193, s36
	v_readfirstlane_b32 s1, v149
	s_nop 3
	s_cmp_eq_u32 s1, 0
	s_cbranch_scc0 .Lga_prio_done
	s_setprio 1

.LBB0_1280:
	v_mov_b64_e32 v[118:119], v[124:125]
	v_exp_f32_e32 v94, v94
	v_exp_f32_e32 v95, v95
	v_exp_f32_e32 v96, v96
	v_exp_f32_e32 v97, v97
	v_exp_f32_e32 v90, v90
	v_exp_f32_e32 v91, v91
	v_exp_f32_e32 v92, v92
	v_exp_f32_e32 v93, v93
	v_cvt_pk_bf16_f32 v160, v94, v95
	v_cvt_pk_bf16_f32 v161, v96, v97
	v_cvt_pk_bf16_f32 v162, v90, v91
	v_cvt_pk_bf16_f32 v163, v92, v93
	s_waitcnt vmcnt(4)
	ds_write_b128 v180, v[58:61] offset:17408
	ds_write_b128 v182, v[62:65] offset:25600
	ds_write_b128 v181, v[66:69] offset:17408
	ds_write_b128 v182, v[70:73] offset:30208
	ds_read2_b64 v[94:97], v176 offset0:64 offset1:68
	v_mfma_f32_16x16x32_bf16 v[38:41], v[190:193], v[160:163], v[38:41]
	v_exp_f32_e32 v102, v102
	v_exp_f32_e32 v103, v103
	v_mfma_f32_16x16x32_bf16 v[30:33], v[212:215], v[160:163], v[30:33]
	v_exp_f32_e32 v104, v104
	v_exp_f32_e32 v105, v105
	v_mfma_f32_16x16x32_bf16 v[22:25], v[244:247], v[160:163], v[22:25]
	v_exp_f32_e32 v98, v98
	v_exp_f32_e32 v99, v99
	s_waitcnt lgkmcnt(0)
	v_mfma_f32_16x16x32_bf16 v[10:13], v[94:97], v[160:163], v[10:13]
	v_exp_f32_e32 v100, v100
	v_exp_f32_e32 v101, v101
	v_cvt_pk_bf16_f32 v166, v102, v103
	v_cvt_pk_bf16_f32 v167, v104, v105
	v_cvt_pk_bf16_f32 v168, v98, v99
	v_cvt_pk_bf16_f32 v169, v100, v101
	ds_read2_b64 v[98:101], v176 offset0:72 offset1:76
	ds_read2_b64 v[102:105], v177 offset0:96 offset1:100
	v_mfma_f32_16x16x32_bf16 v[38:41], v[190:193], v[166:169], v[38:41]
	v_exp_f32_e32 v134, v74
	v_exp_f32_e32 v135, v75
	v_mfma_f32_16x16x32_bf16 v[30:33], v[216:219], v[166:169], v[30:33]
	v_exp_f32_e32 v136, v76
	v_exp_f32_e32 v137, v77
	v_mfma_f32_16x16x32_bf16 v[22:25], v[248:251], v[166:169], v[22:25]
	v_exp_f32_e32 v138, v86
	v_exp_f32_e32 v139, v87
	s_waitcnt lgkmcnt(0)
	v_mfma_f32_16x16x32_bf16 v[6:9], v[102:105], v[160:163], v[6:9]
	v_exp_f32_e32 v140, v88
	v_exp_f32_e32 v141, v89
	v_mfma_f32_16x16x32_bf16 v[10:13], v[98:101], v[166:169], v[10:13]
	v_exp_f32_e32 v122, v78
	v_exp_f32_e32 v123, v79
	v_cvt_pk_bf16_f32 v88, v134, v135
	v_cvt_pk_bf16_f32 v89, v136, v137
	ds_read2_b64 v[134:137], v177 offset0:104 offset1:108
	v_exp_f32_e32 v124, v80
	v_exp_f32_e32 v133, v81
	v_cvt_pk_bf16_f32 v86, v122, v123
	v_cvt_pk_bf16_f32 v87, v124, v133
	s_nop 1
	v_mfma_f32_16x16x32_bf16 v[34:37], v[190:193], v[86:89], v[34:37]
	v_exp_f32_e32 v142, v82
	v_exp_f32_e32 v143, v83
	v_mfma_f32_16x16x32_bf16 v[26:29], v[212:215], v[86:89], v[26:29]
	v_exp_f32_e32 v144, v84
	v_exp_f32_e32 v125, v85
	v_mfma_f32_16x16x32_bf16 v[18:21], v[244:247], v[86:89], v[18:21]
	v_cvt_pk_bf16_f32 v90, v138, v139
	v_cvt_pk_bf16_f32 v91, v140, v141
	v_mfma_f32_16x16x32_bf16 v[14:17], v[94:97], v[86:89], v[14:17]
	v_cvt_pk_bf16_f32 v92, v142, v143
	v_cvt_pk_bf16_f32 v93, v144, v125
	v_mfma_f32_16x16x32_bf16 v[2:5], v[102:105], v[86:89], v[2:5]
	s_nop 0
	v_mfma_f32_16x16x32_bf16 v[34:37], v[190:193], v[90:93], v[34:37]
	v_mfma_f32_16x16x32_bf16 v[26:29], v[216:219], v[90:93], v[26:29]
	v_mfma_f32_16x16x32_bf16 v[18:21], v[248:251], v[90:93], v[18:21]
	v_mfma_f32_16x16x32_bf16 v[14:17], v[98:101], v[90:93], v[14:17]
	s_waitcnt lgkmcnt(0)
	v_mfma_f32_16x16x32_bf16 v[6:9], v[134:137], v[166:169], v[6:9]
	v_mfma_f32_16x16x32_bf16 v[2:5], v[134:137], v[90:93], v[2:5]
	s_cmpk_lg_i32 s0, 0x43
	s_waitcnt lgkmcnt(0)
	s_barrier
	s_cbranch_scc0 .LBB0_1282
	v_mov_b64_e32 v[122:123], v[118:119]
	s_branch .Lga_odd

.Lga_o_1280:
	v_mov_b64_e32 v[118:119], v[124:125]
	v_exp_f32_e32 v94, v94
	v_exp_f32_e32 v95, v95
	v_exp_f32_e32 v96, v96
	v_exp_f32_e32 v97, v97
	v_exp_f32_e32 v90, v90
	v_exp_f32_e32 v91, v91
	v_exp_f32_e32 v92, v92
	v_exp_f32_e32 v93, v93
	v_cvt_pk_bf16_f32 v160, v94, v95
	v_cvt_pk_bf16_f32 v161, v96, v97
	v_cvt_pk_bf16_f32 v162, v90, v91
	v_cvt_pk_bf16_f32 v163, v92, v93
	s_waitcnt vmcnt(4)
	ds_write_b128 v180, v[228:231]
	ds_write_b128 v182, v[232:235] offset:8192
	ds_write_b128 v181, v[236:239]
	ds_write_b128 v182, v[240:243] offset:12800
	ds_read2_b64 v[94:97], v178 offset0:64 offset1:68
	v_mfma_f32_16x16x32_bf16 v[38:41], v[190:193], v[160:163], v[38:41]
	v_exp_f32_e32 v102, v102
	v_exp_f32_e32 v103, v103
	v_mfma_f32_16x16x32_bf16 v[30:33], v[212:215], v[160:163], v[30:33]
	v_exp_f32_e32 v104, v104
	v_exp_f32_e32 v105, v105
	v_mfma_f32_16x16x32_bf16 v[22:25], v[244:247], v[160:163], v[22:25]
	v_exp_f32_e32 v98, v98
	v_exp_f32_e32 v99, v99
	s_waitcnt lgkmcnt(0)
	v_mfma_f32_16x16x32_bf16 v[10:13], v[94:97], v[160:163], v[10:13]
	v_exp_f32_e32 v100, v100
	v_exp_f32_e32 v101, v101
	v_cvt_pk_bf16_f32 v166, v102, v103
	v_cvt_pk_bf16_f32 v167, v104, v105
	v_cvt_pk_bf16_f32 v168, v98, v99
	v_cvt_pk_bf16_f32 v169, v100, v101
	ds_read2_b64 v[98:101], v178 offset0:72 offset1:76
	ds_read2_b64 v[102:105], v179 offset0:96 offset1:100
	v_mfma_f32_16x16x32_bf16 v[38:41], v[190:193], v[166:169], v[38:41]
	v_exp_f32_e32 v134, v74
	v_exp_f32_e32 v135, v75
	v_mfma_f32_16x16x32_bf16 v[30:33], v[216:219], v[166:169], v[30:33]
	v_exp_f32_e32 v136, v76
	v_exp_f32_e32 v137, v77
	v_mfma_f32_16x16x32_bf16 v[22:25], v[248:251], v[166:169], v[22:25]
	v_exp_f32_e32 v138, v86
	v_exp_f32_e32 v139, v87
	s_waitcnt lgkmcnt(0)
	v_mfma_f32_16x16x32_bf16 v[6:9], v[102:105], v[160:163], v[6:9]
	v_exp_f32_e32 v140, v88
	v_exp_f32_e32 v141, v89
	v_mfma_f32_16x16x32_bf16 v[10:13], v[98:101], v[166:169], v[10:13]
	v_exp_f32_e32 v122, v78
	v_exp_f32_e32 v123, v79
	v_cvt_pk_bf16_f32 v88, v134, v135
	v_cvt_pk_bf16_f32 v89, v136, v137
	ds_read2_b64 v[134:137], v179 offset0:104 offset1:108
	v_exp_f32_e32 v124, v80
	v_exp_f32_e32 v133, v81
	v_cvt_pk_bf16_f32 v86, v122, v123
	v_cvt_pk_bf16_f32 v87, v124, v133
	s_nop 1
	v_mfma_f32_16x16x32_bf16 v[34:37], v[190:193], v[86:89], v[34:37]
	v_exp_f32_e32 v142, v82
	v_exp_f32_e32 v143, v83
	v_mfma_f32_16x16x32_bf16 v[26:29], v[212:215], v[86:89], v[26:29]
	v_exp_f32_e32 v144, v84
	v_exp_f32_e32 v125, v85
	v_mfma_f32_16x16x32_bf16 v[18:21], v[244:247], v[86:89], v[18:21]
	v_cvt_pk_bf16_f32 v90, v138, v139
	v_cvt_pk_bf16_f32 v91, v140, v141
	v_mfma_f32_16x16x32_bf16 v[14:17], v[94:97], v[86:89], v[14:17]
	v_cvt_pk_bf16_f32 v92, v142, v143
	v_cvt_pk_bf16_f32 v93, v144, v125
	v_mfma_f32_16x16x32_bf16 v[2:5], v[102:105], v[86:89], v[2:5]
	s_nop 0
	v_mfma_f32_16x16x32_bf16 v[34:37], v[190:193], v[90:93], v[34:37]
	v_mfma_f32_16x16x32_bf16 v[26:29], v[216:219], v[90:93], v[26:29]
	v_mfma_f32_16x16x32_bf16 v[18:21], v[248:251], v[90:93], v[18:21]
	v_mfma_f32_16x16x32_bf16 v[14:17], v[98:101], v[90:93], v[14:17]
	s_waitcnt lgkmcnt(0)
	v_mfma_f32_16x16x32_bf16 v[6:9], v[134:137], v[166:169], v[6:9]
	v_mfma_f32_16x16x32_bf16 v[2:5], v[134:137], v[90:93], v[2:5]
	s_cmpk_lg_i32 s0, 0x43
	s_waitcnt lgkmcnt(0)
	s_barrier
	s_cbranch_scc0 .LBB0_1282
	v_mov_b64_e32 v[122:123], v[118:119]
	s_branch .LBB0_1275
